# attention: ALiBi bias VALU of live steps interleaved into the P.V MFMA sequence before the slot barrier
# speedup vs baseline: 1.0082x; 1.0082x over previous
; template <int D0> __device__ __forceinline__ void pv_one(f32x16& od, int vb, bf16x8 pa0, bf16x8 pa1, bf16x8 pa2, bf16x8 pa3) {
;   const s16x4 l0 = tr_read<v_rd_off(D0, 0, 0)>(vb), h0 = tr_read<v_rd_off(D0, 0, 1)>(vb), l1 = tr_read<v_rd_off(D0, 1, 0)>(vb), h1 = tr_read<v_rd_off(D0, 1, 1)>(vb);
;   const s16x4 l2 = tr_read<v_rd_off(D0, 2, 0)>(vb), h2 = tr_read<v_rd_off(D0, 2, 1)>(vb), l3 = tr_read<v_rd_off(D0, 3, 0)>(vb), h3 = tr_read<v_rd_off(D0, 3, 1)>(vb);
;   asm volatile("s_waitcnt lgkmcnt(0)" ::: "memory"); SBAR();
;     ...
;   od = __builtin_amdgcn_mfma_f32_32x32x16_bf16(pa0, PK(l0, h0), od, 0, 0, 0);
;   od = __builtin_amdgcn_mfma_f32_32x32x16_bf16(pa1, PK(l1, h1), od, 0, 0, 0);
;   od = __builtin_amdgcn_mfma_f32_32x32x16_bf16(pa2, PK(l2, h2), od, 0, 0, 0);
;   od = __builtin_amdgcn_mfma_f32_32x32x16_bf16(pa3, PK(l3, h3), od, 0, 0, 0);
;     ...
; }
; __device__ __forceinline__ void pv_d0(f32x16* o, int vb, bf16x8 pa0, bf16x8 pa1, bf16x8 pa2, bf16x8 pa3) {
;   pv_one<0>(o[0], vb, pa0, pa1, pa2, pa3); pv_one<1>(o[1], vb, pa0, pa1, pa2, pa3); pv_one<2>(o[2], vb, pa0, pa1, pa2, pa3); pv_one<3>(o[3], vb, pa0, pa1, pa2, pa3);
; }
; __device__ __forceinline__ void qkt_c(f32x16& p0, f32x16& p1, const char* Ks, const bf16x8* qr, const f32x16& negm, int r32, int hi) {
; #pragma unroll
;   for (int d0 = 0; d0 < 4; ++d0) { const int cb = (d0 * 16 + hi * 8) * 2;
;     bf16x8 b0 = *reinterpret_cast<const bf16x8*>(Ks + KSWZ(r32, cb));
;     bf16x8 b1 = *reinterpret_cast<const bf16x8*>(Ks + KSWZ(32 + r32, cb));
;     if (d0 == 0) { p0 = __builtin_amdgcn_mfma_f32_32x32x16_bf16(b0, qr[0], negm, 0, 0, 0); p1 = __builtin_amdgcn_mfma_f32_32x32x16_bf16(b1, qr[0], negm, 0, 0, 0); }
;     else { p0 = __builtin_amdgcn_mfma_f32_32x32x16_bf16(b0, qr[d0], p0, 0, 0, 0); p1 = __builtin_amdgcn_mfma_f32_32x32x16_bf16(b1, qr[d0], p1, 0, 0, 0); } }
; }
; template <int R> __device__ __forceinline__ void bias_r(f32x16& p0, f32x16& p1, float dq, float nslope) {
;   constexpr int C0 = (R & 3) + 8 * (R >> 2);
;   float x0, x1, a0 = p0[R], a1 = p1[R];
;   asm("v_sub_f32_e32 %0, %1, %2" : "=v"(x0) : "n"(__builtin_bit_cast(int, (float)C0)), "v"(dq));
;   asm("v_sub_f32_e32 %0, %1, %2" : "=v"(x1) : "n"(__builtin_bit_cast(int, (float)(C0 + 32))), "v"(dq));
;   asm("v_fma_f32 %0, %1, |%2|, %0" : "+v"(a0) : "v"(nslope), "v"(x0));
;   asm("v_fma_f32 %0, %1, |%2|, %0" : "+v"(a1) : "v"(nslope), "v"(x1));
.LBB0_364:
	ds_read_b128 v[114:117], v195 offset:32768
	ds_read_b128 v[204:207], v195 offset:40960
	s_and_b64 vcc, exec, s[14:15]
	s_waitcnt lgkmcnt(1)
	v_mfma_f32_32x32x16_bf16 v[98:113], v[114:117], v[130:133], v[82:97]
	s_waitcnt lgkmcnt(0)
	v_mfma_f32_32x32x16_bf16 v[114:129], v[204:207], v[130:133], v[82:97]
	ds_read_b128 v[204:207], v196 offset:32768
	s_waitcnt lgkmcnt(0)
	v_mfma_f32_32x32x16_bf16 v[98:113], v[204:207], v[134:137], v[98:113]
	ds_read_b128 v[204:207], v196 offset:40960
	s_waitcnt lgkmcnt(0)
	v_mfma_f32_32x32x16_bf16 v[114:129], v[204:207], v[134:137], v[114:129]
	ds_read_b128 v[204:207], v197 offset:32768
	s_waitcnt lgkmcnt(0)
	v_mfma_f32_32x32x16_bf16 v[98:113], v[204:207], v[138:141], v[98:113]
	ds_read_b128 v[204:207], v197 offset:40960
	s_waitcnt lgkmcnt(0)
	v_mfma_f32_32x32x16_bf16 v[114:129], v[204:207], v[138:141], v[114:129]
	ds_read_b128 v[204:207], v198 offset:32768
	s_waitcnt lgkmcnt(0)
	v_mfma_f32_32x32x16_bf16 v[98:113], v[204:207], v[142:145], v[98:113]
	ds_read_b128 v[204:207], v198 offset:40960
	s_waitcnt lgkmcnt(0)
	v_mfma_f32_32x32x16_bf16 v[114:129], v[204:207], v[142:145], v[114:129]
	s_cbranch_vccnz .LBB0_366
	s_add_i32 s72, s22, s46
	s_cmp_lt_i32 s46, s23
	s_cselect_b32 s14, s72, s39
	s_lshl_b32 s14, s14, 6
	v_cvt_f32_i32_e32 v0, s14
	v_sub_f32_e32 v0, v192, v0
	ds_read_b64_tr_b16 v[204:205], v194 offset:0
	ds_read_b64_tr_b16 v[206:207], v194 offset:0x800
	ds_read_b64_tr_b16 v[208:209], v194 offset:0x1000
	ds_read_b64_tr_b16 v[210:211], v194 offset:0x1800
	ds_read_b64_tr_b16 v[212:213], v194 offset:0x2000
	ds_read_b64_tr_b16 v[214:215], v194 offset:0x2800
	ds_read_b64_tr_b16 v[216:217], v194 offset:0x3000
	ds_read_b64_tr_b16 v[218:219], v194 offset:0x3800
	s_waitcnt lgkmcnt(0)
	s_nop 0
	v_mfma_f32_32x32x16_bf16 v[64:79], v[2:5], v[204:207], v[64:79]
	v_sub_f32_e32 v14, 0, v0
	v_sub_f32_e32 v15, 0x42000000, v0
	v_fma_f32 v98, v81, |v14|, v98
	v_sub_f32_e32 v14, 0x3f800000, v0
	ds_read_b64_tr_b16 v[204:205], v194 offset:0x200
	ds_read_b64_tr_b16 v[206:207], v194 offset:0xa00
	v_mfma_f32_32x32x16_bf16 v[64:79], v[6:9], v[208:211], v[64:79]
	v_fma_f32 v114, v81, |v15|, v114
	v_sub_f32_e32 v15, 0x42040000, v0
	v_fma_f32 v99, v81, |v14|, v99
	v_sub_f32_e32 v14, 0x40000000, v0
	ds_read_b64_tr_b16 v[208:209], v194 offset:0x1200
	ds_read_b64_tr_b16 v[210:211], v194 offset:0x1a00
	v_mfma_f32_32x32x16_bf16 v[64:79], v[10:13], v[212:215], v[64:79]
	v_fma_f32 v115, v81, |v15|, v115
	v_sub_f32_e32 v15, 0x42080000, v0
	v_fma_f32 v100, v81, |v14|, v100
	v_sub_f32_e32 v14, 0x40400000, v0
	ds_read_b64_tr_b16 v[212:213], v194 offset:0x2200
	ds_read_b64_tr_b16 v[214:215], v194 offset:0x2a00
	ds_read_b64_tr_b16 v[220:221], v194 offset:0x3200
	ds_read_b64_tr_b16 v[222:223], v194 offset:0x3a00
	s_waitcnt lgkmcnt(0)
	v_mfma_f32_32x32x16_bf16 v[64:79], v[162:165], v[216:219], v[64:79]
	v_fma_f32 v116, v81, |v15|, v116
	v_sub_f32_e32 v15, 0x420c0000, v0
	v_fma_f32 v101, v81, |v14|, v101
	v_sub_f32_e32 v14, 0x41000000, v0
	v_mfma_f32_32x32x16_bf16 v[48:63], v[2:5], v[204:207], v[48:63]
	v_fma_f32 v117, v81, |v15|, v117
	v_sub_f32_e32 v15, 0x42200000, v0
	v_fma_f32 v102, v81, |v14|, v102
	v_sub_f32_e32 v14, 0x41100000, v0
	ds_read_b64_tr_b16 v[204:205], v194 offset:0x400
	ds_read_b64_tr_b16 v[206:207], v194 offset:0xc00
	v_mfma_f32_32x32x16_bf16 v[48:63], v[6:9], v[208:211], v[48:63]
	v_fma_f32 v118, v81, |v15|, v118
	v_sub_f32_e32 v15, 0x42240000, v0
	v_fma_f32 v103, v81, |v14|, v103
	v_sub_f32_e32 v14, 0x41200000, v0
	ds_read_b64_tr_b16 v[208:209], v194 offset:0x1400
	ds_read_b64_tr_b16 v[210:211], v194 offset:0x1c00
	v_mfma_f32_32x32x16_bf16 v[48:63], v[10:13], v[212:215], v[48:63]
	v_fma_f32 v119, v81, |v15|, v119
	v_sub_f32_e32 v15, 0x42280000, v0
	v_fma_f32 v104, v81, |v14|, v104
	v_sub_f32_e32 v14, 0x41300000, v0
	ds_read_b64_tr_b16 v[212:213], v194 offset:0x2400
	ds_read_b64_tr_b16 v[214:215], v194 offset:0x2c00
	ds_read_b64_tr_b16 v[216:217], v194 offset:0x3400
	ds_read_b64_tr_b16 v[218:219], v194 offset:0x3c00
	s_waitcnt lgkmcnt(0)
	v_mfma_f32_32x32x16_bf16 v[48:63], v[162:165], v[220:223], v[48:63]
	v_fma_f32 v120, v81, |v15|, v120
	v_sub_f32_e32 v15, 0x422c0000, v0
	v_fma_f32 v105, v81, |v14|, v105
	v_sub_f32_e32 v14, 0x41800000, v0
	v_mfma_f32_32x32x16_bf16 v[32:47], v[2:5], v[204:207], v[32:47]
	v_fma_f32 v121, v81, |v15|, v121
	v_sub_f32_e32 v15, 0x42400000, v0
	v_fma_f32 v106, v81, |v14|, v106
	v_sub_f32_e32 v14, 0x41880000, v0
	ds_read_b64_tr_b16 v[204:205], v194 offset:0x600
	ds_read_b64_tr_b16 v[206:207], v194 offset:0xe00
	v_mfma_f32_32x32x16_bf16 v[32:47], v[6:9], v[208:211], v[32:47]
	v_fma_f32 v122, v81, |v15|, v122
	v_sub_f32_e32 v15, 0x42440000, v0
	v_fma_f32 v107, v81, |v14|, v107
	v_sub_f32_e32 v14, 0x41900000, v0
	ds_read_b64_tr_b16 v[208:209], v194 offset:0x1600
	ds_read_b64_tr_b16 v[210:211], v194 offset:0x1e00
	v_mfma_f32_32x32x16_bf16 v[32:47], v[10:13], v[212:215], v[32:47]
	v_fma_f32 v123, v81, |v15|, v123
	v_sub_f32_e32 v15, 0x42480000, v0
	v_fma_f32 v108, v81, |v14|, v108
	v_sub_f32_e32 v14, 0x41980000, v0
	ds_read_b64_tr_b16 v[212:213], v194 offset:0x2600
	ds_read_b64_tr_b16 v[214:215], v194 offset:0x2e00
	ds_read_b64_tr_b16 v[220:221], v194 offset:0x3600
	ds_read_b64_tr_b16 v[222:223], v194 offset:0x3e00
	s_waitcnt lgkmcnt(0)
	v_mfma_f32_32x32x16_bf16 v[32:47], v[162:165], v[216:219], v[32:47]
	v_fma_f32 v124, v81, |v15|, v124
	v_sub_f32_e32 v15, 0x424c0000, v0
	v_fma_f32 v109, v81, |v14|, v109
	v_sub_f32_e32 v14, 0x41c00000, v0
	v_mfma_f32_32x32x16_bf16 v[16:31], v[2:5], v[204:207], v[16:31]
	v_fma_f32 v125, v81, |v15|, v125
	v_sub_f32_e32 v15, 0x42600000, v0
	v_fma_f32 v110, v81, |v14|, v110
	v_sub_f32_e32 v14, 0x41c80000, v0
	v_mfma_f32_32x32x16_bf16 v[16:31], v[6:9], v[208:211], v[16:31]
	v_fma_f32 v126, v81, |v15|, v126
	v_sub_f32_e32 v15, 0x42640000, v0
	v_fma_f32 v111, v81, |v14|, v111
	v_sub_f32_e32 v14, 0x41d00000, v0
	v_mfma_f32_32x32x16_bf16 v[16:31], v[10:13], v[212:215], v[16:31]
	v_fma_f32 v127, v81, |v15|, v127
	v_sub_f32_e32 v15, 0x42680000, v0
	v_fma_f32 v112, v81, |v14|, v112
	v_sub_f32_e32 v14, 0x41d80000, v0
	v_mfma_f32_32x32x16_bf16 v[16:31], v[162:165], v[220:223], v[16:31]
	v_sub_f32_e32 v0, 0x426c0000, v0
	v_fma_f32 v128, v81, |v15|, v128
	v_fma_f32 v113, v81, |v14|, v113
	v_fma_f32 v129, v81, |v0|, v129
	s_barrier
	s_branch .Lafter_bias_0

; __device__ __forceinline__ bool softmax_pp(f32x16& p0, f32x16& p1, float& m_reg, float& l_reg, f32x16& negm, float& alpha, float& m_run, float dq, float nslope,
;                                            bf16x8& pa0, bf16x8& pa1, bf16x8& pa2, bf16x8& pa3) {
;     ...
;   float a = fmaxf(fmaxf(p0[0], p0[1]), p1[0]), bq = fmaxf(fmaxf(p0[2], p0[3]), p1[1]); a = fmaxf(fmaxf(a, p1[2]), p1[3]);
; #pragma unroll
;   for (int r = 4; r < 16; r += 4) { a = fmaxf(fmaxf(a, p0[r]), p0[r + 1]); bq = fmaxf(fmaxf(bq, p0[r + 2]), p0[r + 3]); a = fmaxf(fmaxf(a, p1[r]), p1[r + 1]); bq = fmaxf(fmaxf(bq, p1[r + 2]), p1[r + 3]); }
;   float pmax = fmaxf(a, bq);
;   { auto rr = __builtin_amdgcn_permlane32_swap(__float_as_uint(pmax), __float_as_uint(pmax), false, false);
;     pmax = fmaxf(__uint_as_float(rr[0]), __uint_as_float(rr[1])); }
;   alpha = 1.f;
;   { const float tmax = pmax + m_reg;
;     if (__all(tmax < m_run - TSKIP)) return false;
;     m_run = fmaxf(m_run, tmax); }
;   if (__builtin_expect(!__all(pmax <= THRL), 0)) { const float dl = fmaxf(pmax, 0.f); m_reg += dl; alpha = __builtin_amdgcn_exp2f(-dl);
.Lafter_bias_0:
	v_max_f32_e32 v0, v99, v99
	v_max_f32_e32 v14, v98, v98
	v_max_f32_e32 v0, v14, v0
	v_max3_f32 v14, v100, v101, v115
	v_max3_f32 v0, v0, v114, v116
	v_max3_f32 v0, v0, v117, v102
	v_max3_f32 v14, v14, v104, v105
	v_max3_f32 v0, v0, v103, v118
	v_max3_f32 v14, v14, v120, v121
	v_max3_f32 v0, v0, v119, v106
	v_max3_f32 v14, v14, v108, v109
	v_max3_f32 v0, v0, v107, v122
	v_max3_f32 v14, v14, v124, v125
	v_max3_f32 v0, v0, v123, v110
	v_max3_f32 v14, v14, v112, v113
	v_max3_f32 v0, v0, v111, v126
	v_max3_f32 v14, v14, v128, v129
	v_max3_f32 v0, v0, v127, v14
	v_mov_b32_e32 v14, v0
	s_nop 1
	v_permlane32_swap_b32_e32 v0, v14
	v_max_f32_e32 v14, v14, v14
	v_max_f32_e32 v0, v0, v0
	v_max_f32_e32 v167, v0, v14
	v_pk_add_f32 v[14:15], v[172:173], v[166:167]
	s_nop 0
	v_cmp_lt_f32_e32 vcc, v15, v14
	s_cmp_lg_u64 vcc, exec
	s_cselect_b64 s[14:15], -1, 0
	s_cmp_eq_u64 vcc, exec
	s_cbranch_scc1 .LBB0_370
	v_cmp_ge_f32_e32 vcc, s59, v167
	s_cmp_eq_u64 vcc, exec
	s_cbranch_scc0 .LBB0_395
	v_mov_b32_e32 v0, 1.0

; template <int D0> __device__ __forceinline__ void pv_one(f32x16& od, int vb, bf16x8 pa0, bf16x8 pa1, bf16x8 pa2, bf16x8 pa3) {
;   const s16x4 l0 = tr_read<v_rd_off(D0, 0, 0)>(vb), h0 = tr_read<v_rd_off(D0, 0, 1)>(vb), l1 = tr_read<v_rd_off(D0, 1, 0)>(vb), h1 = tr_read<v_rd_off(D0, 1, 1)>(vb);
;   const s16x4 l2 = tr_read<v_rd_off(D0, 2, 0)>(vb), h2 = tr_read<v_rd_off(D0, 2, 1)>(vb), l3 = tr_read<v_rd_off(D0, 3, 0)>(vb), h3 = tr_read<v_rd_off(D0, 3, 1)>(vb);
;   asm volatile("s_waitcnt lgkmcnt(0)" ::: "memory"); SBAR();
;     ...
;   od = __builtin_amdgcn_mfma_f32_32x32x16_bf16(pa0, PK(l0, h0), od, 0, 0, 0);
;   od = __builtin_amdgcn_mfma_f32_32x32x16_bf16(pa1, PK(l1, h1), od, 0, 0, 0);
;   od = __builtin_amdgcn_mfma_f32_32x32x16_bf16(pa2, PK(l2, h2), od, 0, 0, 0);
;   od = __builtin_amdgcn_mfma_f32_32x32x16_bf16(pa3, PK(l3, h3), od, 0, 0, 0);
;     ...
; }
; __device__ __forceinline__ void pv_d0(f32x16* o, int vb, bf16x8 pa0, bf16x8 pa1, bf16x8 pa2, bf16x8 pa3) {
;   pv_one<0>(o[0], vb, pa0, pa1, pa2, pa3); pv_one<1>(o[1], vb, pa0, pa1, pa2, pa3); pv_one<2>(o[2], vb, pa0, pa1, pa2, pa3); pv_one<3>(o[3], vb, pa0, pa1, pa2, pa3);
; }
; __device__ __forceinline__ void qkt_c(f32x16& p0, f32x16& p1, const char* Ks, const bf16x8* qr, const f32x16& negm, int r32, int hi) {
; #pragma unroll
;   for (int d0 = 0; d0 < 4; ++d0) { const int cb = (d0 * 16 + hi * 8) * 2;
;     bf16x8 b0 = *reinterpret_cast<const bf16x8*>(Ks + KSWZ(r32, cb));
;     bf16x8 b1 = *reinterpret_cast<const bf16x8*>(Ks + KSWZ(32 + r32, cb));
;     if (d0 == 0) { p0 = __builtin_amdgcn_mfma_f32_32x32x16_bf16(b0, qr[0], negm, 0, 0, 0); p1 = __builtin_amdgcn_mfma_f32_32x32x16_bf16(b1, qr[0], negm, 0, 0, 0); }
;     else { p0 = __builtin_amdgcn_mfma_f32_32x32x16_bf16(b0, qr[d0], p0, 0, 0, 0); p1 = __builtin_amdgcn_mfma_f32_32x32x16_bf16(b1, qr[d0], p1, 0, 0, 0); } }
; }
; template <int R> __device__ __forceinline__ void bias_r(f32x16& p0, f32x16& p1, float dq, float nslope) {
;   constexpr int C0 = (R & 3) + 8 * (R >> 2);
;   float x0, x1, a0 = p0[R], a1 = p1[R];
;   asm("v_sub_f32_e32 %0, %1, %2" : "=v"(x0) : "n"(__builtin_bit_cast(int, (float)C0)), "v"(dq));
;   asm("v_sub_f32_e32 %0, %1, %2" : "=v"(x1) : "n"(__builtin_bit_cast(int, (float)(C0 + 32))), "v"(dq));
;   asm("v_fma_f32 %0, %1, |%2|, %0" : "+v"(a0) : "v"(nslope), "v"(x0));
;   asm("v_fma_f32 %0, %1, |%2|, %0" : "+v"(a1) : "v"(nslope), "v"(x1));
.LBB0_379:
	s_waitcnt lgkmcnt(0)
	s_barrier
	ds_read_b128 v[114:117], v195 offset:49152
	ds_read_b128 v[204:207], v195 offset:57344
	s_andn2_b64 vcc, exec, s[14:15]
	s_waitcnt lgkmcnt(1)
	v_mfma_f32_32x32x16_bf16 v[98:113], v[114:117], v[130:133], v[82:97]
	s_waitcnt lgkmcnt(0)
	v_mfma_f32_32x32x16_bf16 v[114:129], v[204:207], v[130:133], v[82:97]
	ds_read_b128 v[204:207], v196 offset:49152
	s_waitcnt lgkmcnt(0)
	v_mfma_f32_32x32x16_bf16 v[98:113], v[204:207], v[134:137], v[98:113]
	ds_read_b128 v[204:207], v196 offset:57344
	s_waitcnt lgkmcnt(0)
	v_mfma_f32_32x32x16_bf16 v[114:129], v[204:207], v[134:137], v[114:129]
	ds_read_b128 v[204:207], v197 offset:49152
	s_waitcnt lgkmcnt(0)
	v_mfma_f32_32x32x16_bf16 v[98:113], v[204:207], v[138:141], v[98:113]
	ds_read_b128 v[204:207], v197 offset:57344
	s_waitcnt lgkmcnt(0)
	v_mfma_f32_32x32x16_bf16 v[114:129], v[204:207], v[138:141], v[114:129]
	ds_read_b128 v[204:207], v198 offset:49152
	s_waitcnt lgkmcnt(0)
	v_mfma_f32_32x32x16_bf16 v[98:113], v[204:207], v[142:145], v[98:113]
	ds_read_b128 v[204:207], v198 offset:57344
	s_waitcnt lgkmcnt(0)
	v_mfma_f32_32x32x16_bf16 v[114:129], v[204:207], v[142:145], v[114:129]
	s_cbranch_vccnz .LBB0_381
	s_add_i32 s46, s47, -1
	s_add_i32 s72, s72, 1
	s_add_i32 s14, s39, -1
	s_cmp_lt_i32 s46, s23
	s_cselect_b32 s14, s72, s14
	s_lshl_b32 s14, s14, 6
	v_cvt_f32_i32_e32 v0, s14
	v_sub_f32_e32 v0, v192, v0
	ds_read_b64_tr_b16 v[204:205], v193 offset:0
	ds_read_b64_tr_b16 v[206:207], v193 offset:0x800
	ds_read_b64_tr_b16 v[208:209], v193 offset:0x1000
	ds_read_b64_tr_b16 v[210:211], v193 offset:0x1800
	ds_read_b64_tr_b16 v[212:213], v193 offset:0x2000
	ds_read_b64_tr_b16 v[214:215], v193 offset:0x2800
	ds_read_b64_tr_b16 v[216:217], v193 offset:0x3000
	ds_read_b64_tr_b16 v[218:219], v193 offset:0x3800
	s_waitcnt lgkmcnt(0)
	s_nop 0
	v_mfma_f32_32x32x16_bf16 v[64:79], v[2:5], v[204:207], v[64:79]
	v_sub_f32_e32 v14, 0, v0
	v_sub_f32_e32 v15, 0x42000000, v0
	v_fma_f32 v98, v81, |v14|, v98
	v_sub_f32_e32 v14, 0x3f800000, v0
	ds_read_b64_tr_b16 v[204:205], v193 offset:0x200
	ds_read_b64_tr_b16 v[206:207], v193 offset:0xa00
	v_mfma_f32_32x32x16_bf16 v[64:79], v[6:9], v[208:211], v[64:79]
	v_fma_f32 v114, v81, |v15|, v114
	v_sub_f32_e32 v15, 0x42040000, v0
	v_fma_f32 v99, v81, |v14|, v99
	v_sub_f32_e32 v14, 0x40000000, v0
	ds_read_b64_tr_b16 v[208:209], v193 offset:0x1200
	ds_read_b64_tr_b16 v[210:211], v193 offset:0x1a00
	v_mfma_f32_32x32x16_bf16 v[64:79], v[10:13], v[212:215], v[64:79]
	v_fma_f32 v115, v81, |v15|, v115
	v_sub_f32_e32 v15, 0x42080000, v0
	v_fma_f32 v100, v81, |v14|, v100
	v_sub_f32_e32 v14, 0x40400000, v0
	ds_read_b64_tr_b16 v[212:213], v193 offset:0x2200
	ds_read_b64_tr_b16 v[214:215], v193 offset:0x2a00
	ds_read_b64_tr_b16 v[220:221], v193 offset:0x3200
	ds_read_b64_tr_b16 v[222:223], v193 offset:0x3a00
	s_waitcnt lgkmcnt(0)
	v_mfma_f32_32x32x16_bf16 v[64:79], v[162:165], v[216:219], v[64:79]
	v_fma_f32 v116, v81, |v15|, v116
	v_sub_f32_e32 v15, 0x420c0000, v0
	v_fma_f32 v101, v81, |v14|, v101
	v_sub_f32_e32 v14, 0x41000000, v0
	v_mfma_f32_32x32x16_bf16 v[48:63], v[2:5], v[204:207], v[48:63]
	v_fma_f32 v117, v81, |v15|, v117
	v_sub_f32_e32 v15, 0x42200000, v0
	v_fma_f32 v102, v81, |v14|, v102
	v_sub_f32_e32 v14, 0x41100000, v0
	ds_read_b64_tr_b16 v[204:205], v193 offset:0x400
	ds_read_b64_tr_b16 v[206:207], v193 offset:0xc00
	v_mfma_f32_32x32x16_bf16 v[48:63], v[6:9], v[208:211], v[48:63]
	v_fma_f32 v118, v81, |v15|, v118
	v_sub_f32_e32 v15, 0x42240000, v0
	v_fma_f32 v103, v81, |v14|, v103
	v_sub_f32_e32 v14, 0x41200000, v0
	ds_read_b64_tr_b16 v[208:209], v193 offset:0x1400
	ds_read_b64_tr_b16 v[210:211], v193 offset:0x1c00
	v_mfma_f32_32x32x16_bf16 v[48:63], v[10:13], v[212:215], v[48:63]
	v_fma_f32 v119, v81, |v15|, v119
	v_sub_f32_e32 v15, 0x42280000, v0
	v_fma_f32 v104, v81, |v14|, v104
	v_sub_f32_e32 v14, 0x41300000, v0
	ds_read_b64_tr_b16 v[212:213], v193 offset:0x2400
	ds_read_b64_tr_b16 v[214:215], v193 offset:0x2c00
	ds_read_b64_tr_b16 v[216:217], v193 offset:0x3400
	ds_read_b64_tr_b16 v[218:219], v193 offset:0x3c00
	s_waitcnt lgkmcnt(0)
	v_mfma_f32_32x32x16_bf16 v[48:63], v[162:165], v[220:223], v[48:63]
	v_fma_f32 v120, v81, |v15|, v120
	v_sub_f32_e32 v15, 0x422c0000, v0
	v_fma_f32 v105, v81, |v14|, v105
	v_sub_f32_e32 v14, 0x41800000, v0
	v_mfma_f32_32x32x16_bf16 v[32:47], v[2:5], v[204:207], v[32:47]
	v_fma_f32 v121, v81, |v15|, v121
	v_sub_f32_e32 v15, 0x42400000, v0
	v_fma_f32 v106, v81, |v14|, v106
	v_sub_f32_e32 v14, 0x41880000, v0
	ds_read_b64_tr_b16 v[204:205], v193 offset:0x600
	ds_read_b64_tr_b16 v[206:207], v193 offset:0xe00
	v_mfma_f32_32x32x16_bf16 v[32:47], v[6:9], v[208:211], v[32:47]
	v_fma_f32 v122, v81, |v15|, v122
	v_sub_f32_e32 v15, 0x42440000, v0
	v_fma_f32 v107, v81, |v14|, v107
	v_sub_f32_e32 v14, 0x41900000, v0
	ds_read_b64_tr_b16 v[208:209], v193 offset:0x1600
	ds_read_b64_tr_b16 v[210:211], v193 offset:0x1e00
	v_mfma_f32_32x32x16_bf16 v[32:47], v[10:13], v[212:215], v[32:47]
	v_fma_f32 v123, v81, |v15|, v123
	v_sub_f32_e32 v15, 0x42480000, v0
	v_fma_f32 v108, v81, |v14|, v108
	v_sub_f32_e32 v14, 0x41980000, v0
	ds_read_b64_tr_b16 v[212:213], v193 offset:0x2600
	ds_read_b64_tr_b16 v[214:215], v193 offset:0x2e00
	ds_read_b64_tr_b16 v[220:221], v193 offset:0x3600
	ds_read_b64_tr_b16 v[222:223], v193 offset:0x3e00
	s_waitcnt lgkmcnt(0)
	v_mfma_f32_32x32x16_bf16 v[32:47], v[162:165], v[216:219], v[32:47]
	v_fma_f32 v124, v81, |v15|, v124
	v_sub_f32_e32 v15, 0x424c0000, v0
	v_fma_f32 v109, v81, |v14|, v109
	v_sub_f32_e32 v14, 0x41c00000, v0
	v_mfma_f32_32x32x16_bf16 v[16:31], v[2:5], v[204:207], v[16:31]
	v_fma_f32 v125, v81, |v15|, v125
	v_sub_f32_e32 v15, 0x42600000, v0
	v_fma_f32 v110, v81, |v14|, v110
	v_sub_f32_e32 v14, 0x41c80000, v0
	v_mfma_f32_32x32x16_bf16 v[16:31], v[6:9], v[208:211], v[16:31]
	v_fma_f32 v126, v81, |v15|, v126
	v_sub_f32_e32 v15, 0x42640000, v0
	v_fma_f32 v111, v81, |v14|, v111
	v_sub_f32_e32 v14, 0x41d00000, v0
	v_mfma_f32_32x32x16_bf16 v[16:31], v[10:13], v[212:215], v[16:31]
	v_fma_f32 v127, v81, |v15|, v127
	v_sub_f32_e32 v15, 0x42680000, v0
	v_fma_f32 v112, v81, |v14|, v112
	v_sub_f32_e32 v14, 0x41d80000, v0
	v_mfma_f32_32x32x16_bf16 v[16:31], v[162:165], v[220:223], v[16:31]
	v_sub_f32_e32 v0, 0x426c0000, v0
	v_fma_f32 v128, v81, |v15|, v128
	v_fma_f32 v113, v81, |v14|, v113
	v_fma_f32 v129, v81, |v0|, v129
	s_barrier
	s_branch .Lafter_bias_1

; __device__ __forceinline__ bool softmax_pp(f32x16& p0, f32x16& p1, float& m_reg, float& l_reg, f32x16& negm, float& alpha, float& m_run, float dq, float nslope,
;                                            bf16x8& pa0, bf16x8& pa1, bf16x8& pa2, bf16x8& pa3) {
;     ...
;   float a = fmaxf(fmaxf(p0[0], p0[1]), p1[0]), bq = fmaxf(fmaxf(p0[2], p0[3]), p1[1]); a = fmaxf(fmaxf(a, p1[2]), p1[3]);
; #pragma unroll
;   for (int r = 4; r < 16; r += 4) { a = fmaxf(fmaxf(a, p0[r]), p0[r + 1]); bq = fmaxf(fmaxf(bq, p0[r + 2]), p0[r + 3]); a = fmaxf(fmaxf(a, p1[r]), p1[r + 1]); bq = fmaxf(fmaxf(bq, p1[r + 2]), p1[r + 3]); }
;   float pmax = fmaxf(a, bq);
;   { auto rr = __builtin_amdgcn_permlane32_swap(__float_as_uint(pmax), __float_as_uint(pmax), false, false);
;     pmax = fmaxf(__uint_as_float(rr[0]), __uint_as_float(rr[1])); }
;   alpha = 1.f;
;   { const float tmax = pmax + m_reg;
;     if (__all(tmax < m_run - TSKIP)) return false;
;     m_run = fmaxf(m_run, tmax); }
;   if (__builtin_expect(!__all(pmax <= THRL), 0)) { const float dl = fmaxf(pmax, 0.f); m_reg += dl; alpha = __builtin_amdgcn_exp2f(-dl);
.Lafter_bias_1:
	v_max_f32_e32 v0, v99, v99
	v_max_f32_e32 v14, v98, v98
	v_max_f32_e32 v0, v14, v0
	v_max3_f32 v14, v100, v101, v115
	v_max3_f32 v0, v0, v114, v116
	v_max3_f32 v0, v0, v117, v102
	v_max3_f32 v14, v14, v104, v105
	v_max3_f32 v0, v0, v103, v118
	v_max3_f32 v14, v14, v120, v121
	v_max3_f32 v0, v0, v119, v106
	v_max3_f32 v14, v14, v108, v109
	v_max3_f32 v0, v0, v107, v122
	v_max3_f32 v14, v14, v124, v125
	v_max3_f32 v0, v0, v123, v110
	v_max3_f32 v14, v14, v112, v113
	v_max3_f32 v0, v0, v111, v126
	v_max3_f32 v14, v14, v128, v129
	v_max3_f32 v0, v0, v127, v14
	v_mov_b32_e32 v14, v0
	s_nop 1
	v_permlane32_swap_b32_e32 v0, v14
	v_max_f32_e32 v14, v14, v14
	v_max_f32_e32 v0, v0, v0
	v_max_f32_e32 v167, v0, v14
	v_pk_add_f32 v[14:15], v[172:173], v[166:167]
	v_mov_b32_e32 v0, 1.0
	v_cmp_lt_f32_e32 vcc, v15, v14
	s_cmp_lg_u64 vcc, exec
	s_cselect_b64 s[14:15], -1, 0
	s_cmp_eq_u64 vcc, exec
	s_cbranch_scc1 .LBB0_385
	v_cmp_ge_f32_e32 vcc, s59, v167
	s_cmp_eq_u64 vcc, exec
	s_cbranch_scc0 .LBB0_396
	v_mov_b32_e32 v0, 1.0
